# v26 + EpiNorm XN-store part: the 8 per-row scale values read from LDS once (were 16 dependent single reads), v_mov into the original registers with the store-data hazard pad
# speedup vs baseline: 1.0066x; 1.0011x over previous
; __device__ __forceinline__ unsigned pk2(float lo, float hi) { f32x2 v = {lo, hi}; bf16x2_t b = __builtin_convertvector(v, bf16x2_t); return __builtin_bit_cast(unsigned, b); }
;     __device__ __forceinline__ void operator()(f32x4 (&acc)[2][2][4][2], const Unit& u, int wr, int wc, int fr, int fq) const {
;     ...
; #pragma unroll
;         for (int bj = 0; bj < 2; ++bj) {
;             const int col = u.pn * BM + bj * HALF + wc * 32 + 8 * fq;
;             f32x4 mp[2], sh[2];
; #pragma unroll
;             for (int n = 0; n < 2; ++n) { mp[n] = *(const f32x4*)(gpre + col + 4 * n) * (*(const f32x4*)(md + sc_off + col + 4 * n) + 1.0f); sh[n] = *(const f32x4*)(md + sh_off + col + 4 * n); }
; #pragma unroll
;             for (int ai = 0; ai < 2; ++ai)
; #pragma unroll
;                 for (int m = 0; m < 4; ++m) {
;                     const int rl = ai * HALF + wr * 64 + m * 16 + fr; const float r = S[rl];
;                     const f32x4 h0 = (acc[ai][bj][m][0] * r) * mp[0] + sh[0], h1 = (acc[ai][bj][m][1] * r) * mp[1] + sh[1];
;                     u32x4 w; w.x = pk2(h0[0], h0[1]); w.y = pk2(h0[2], h0[3]); w.z = pk2(h1[0], h1[1]); w.w = pk2(h1[2], h1[3]);
;                     *(u32x4*)(XN + (size_t)(u.pm * BM + rl) * DM + col) = w;
;                 }
.LBB0_978:
	s_or_b64 exec, exec, s[8:9]
	s_add_u32 s8, s53, 0x4000
	s_addc_u32 s9, s64, 0
	s_waitcnt vmcnt(0) lgkmcnt(0)
	s_barrier
	ds_read_b32 v192, v234
	ds_read_b32 v193, v235
	ds_read_b32 v194, v236
	ds_read_b32 v195, v242
	ds_read_b32 v196, v243
	ds_read_b32 v197, v244
	ds_read_b32 v198, v245
	ds_read_b32 v199, v246
	s_waitcnt lgkmcnt(0)
	v_lshl_add_u64 v[184:185], s[16:17], 0, v[182:183]
	v_lshl_add_u64 v[30:31], s[8:9], 0, v[182:183]
	global_load_dwordx4 v[170:173], v[184:185], off offset:16
	s_waitcnt lgkmcnt(0)
	global_load_dwordx4 v[26:29], v[184:185], off
	global_load_dwordx4 v[188:191], v[30:31], off offset:16
	s_nop 0
	global_load_dwordx4 v[30:33], v[30:31], off
	s_add_u32 s40, s53, 0x3000
	s_addc_u32 s41, s64, 0
	v_lshl_add_u64 v[174:175], s[40:41], 0, v[182:183]
	s_waitcnt vmcnt(1)
	v_pk_add_f32 v[176:177], v[188:189], 1.0 op_sel_hi:[1,0]
	s_waitcnt vmcnt(0)
	v_pk_add_f32 v[32:33], v[32:33], 1.0 op_sel_hi:[1,0]
	v_pk_add_f32 v[30:31], v[30:31], 1.0 op_sel_hi:[1,0]
	v_pk_mul_f32 v[182:183], v[28:29], v[32:33]
	v_pk_mul_f32 v[186:187], v[26:27], v[30:31]
	global_load_dwordx4 v[26:29], v[174:175], off offset:16
	global_load_dwordx4 v[30:33], v[174:175], off
	v_pk_add_f32 v[174:175], v[190:191], 1.0 op_sel_hi:[1,0]
	v_pk_mul_f32 v[190:191], v[170:171], v[176:177]
	s_nop 1
	v_mov_b32_e32 v170, v192
	v_pk_mul_f32 v[188:189], v[172:173], v[174:175]
	s_waitcnt lgkmcnt(0)
	v_pk_mul_f32 v[106:107], v[106:107], v[170:171] op_sel_hi:[1,0]
	v_pk_mul_f32 v[108:109], v[108:109], v[170:171] op_sel_hi:[1,0]
	v_pk_mul_f32 v[116:117], v[116:117], v[170:171] op_sel_hi:[1,0]
	v_pk_mul_f32 v[114:115], v[114:115], v[170:171] op_sel_hi:[1,0]
	s_waitcnt vmcnt(1)
	v_pk_fma_f32 v[170:171], v[188:189], v[116:117], v[28:29]
	s_waitcnt vmcnt(0)
	v_pk_fma_f32 v[106:107], v[186:187], v[106:107], v[30:31]
	v_pk_fma_f32 v[108:109], v[182:183], v[108:109], v[32:33]
	v_pk_fma_f32 v[116:117], v[190:191], v[114:115], v[26:27]
	v_cvt_pk_bf16_f32 v114, v106, v107
	v_lshlrev_b64 v[106:107], 11, v[180:181]
	v_cvt_pk_bf16_f32 v115, v108, v109
	v_lshl_add_u64 v[106:107], s[74:75], 0, v[106:107]
	v_lshlrev_b64 v[108:109], 1, v[178:179]
	v_cvt_pk_bf16_f32 v116, v116, v117
	v_cvt_pk_bf16_f32 v117, v170, v171
	v_lshl_add_u64 v[106:107], v[106:107], 0, v[108:109]
	global_store_dwordx4 v[106:107], v[114:117], off
	s_nop 1
	v_mov_b32_e32 v114, v193
	s_waitcnt lgkmcnt(0)
	v_pk_mul_f32 v[100:101], v[100:101], v[114:115] op_sel_hi:[1,0]
	v_pk_mul_f32 v[98:99], v[98:99], v[114:115] op_sel_hi:[1,0]
	v_pk_mul_f32 v[110:111], v[110:111], v[114:115] op_sel_hi:[1,0]
	v_pk_fma_f32 v[100:101], v[182:183], v[100:101], v[32:33]
	v_pk_fma_f32 v[98:99], v[186:187], v[98:99], v[30:31]
	v_pk_fma_f32 v[110:111], v[190:191], v[110:111], v[26:27]
	v_pk_mul_f32 v[112:113], v[112:113], v[114:115] op_sel_hi:[1,0]
	v_cvt_pk_bf16_f32 v98, v98, v99
	v_cvt_pk_bf16_f32 v99, v100, v101
	v_cvt_pk_bf16_f32 v100, v110, v111
	v_lshlrev_b64 v[110:111], 11, v[164:165]
	v_pk_fma_f32 v[112:113], v[188:189], v[112:113], v[28:29]
	v_lshl_add_u64 v[110:111], s[74:75], 0, v[110:111]
	v_cvt_pk_bf16_f32 v101, v112, v113
	v_lshl_add_u64 v[110:111], v[110:111], 0, v[108:109]
	global_store_dwordx4 v[110:111], v[98:101], off
	s_nop 1
	v_mov_b32_e32 v98, v194
	s_waitcnt lgkmcnt(0)
	v_pk_mul_f32 v[96:97], v[96:97], v[98:99] op_sel_hi:[1,0]
	v_pk_mul_f32 v[94:95], v[94:95], v[98:99] op_sel_hi:[1,0]
	v_pk_mul_f32 v[100:101], v[104:105], v[98:99] op_sel_hi:[1,0]
	v_pk_mul_f32 v[98:99], v[102:103], v[98:99] op_sel_hi:[1,0]
	v_pk_fma_f32 v[96:97], v[182:183], v[96:97], v[32:33]
	v_pk_fma_f32 v[94:95], v[186:187], v[94:95], v[30:31]
	v_pk_fma_f32 v[98:99], v[190:191], v[98:99], v[26:27]
	v_cvt_pk_bf16_f32 v94, v94, v95
	v_cvt_pk_bf16_f32 v95, v96, v97
	v_cvt_pk_bf16_f32 v96, v98, v99
	v_lshlrev_b64 v[98:99], 11, v[162:163]
	v_pk_fma_f32 v[100:101], v[188:189], v[100:101], v[28:29]
	v_lshl_add_u64 v[98:99], s[74:75], 0, v[98:99]
	v_cvt_pk_bf16_f32 v97, v100, v101
	v_lshl_add_u64 v[98:99], v[98:99], 0, v[108:109]
	global_store_dwordx4 v[98:99], v[94:97], off
	s_nop 1
	v_mov_b32_e32 v94, v195
	s_waitcnt lgkmcnt(0)
	v_pk_mul_f32 v[92:93], v[92:93], v[94:95] op_sel_hi:[1,0]
	v_pk_mul_f32 v[90:91], v[90:91], v[94:95] op_sel_hi:[1,0]
	v_pk_fma_f32 v[96:97], v[182:183], v[92:93], v[32:33]
	v_pk_fma_f32 v[90:91], v[186:187], v[90:91], v[30:31]
	v_pk_mul_f32 v[92:93], v[128:129], v[94:95] op_sel_hi:[1,0]
	v_pk_mul_f32 v[94:95], v[126:127], v[94:95] op_sel_hi:[1,0]
	v_pk_fma_f32 v[100:101], v[188:189], v[92:93], v[28:29]
	v_cvt_pk_bf16_f32 v92, v90, v91
	v_lshlrev_b64 v[90:91], 11, v[160:161]
	v_pk_fma_f32 v[94:95], v[190:191], v[94:95], v[26:27]
	v_lshl_add_u64 v[90:91], s[74:75], 0, v[90:91]
	v_cvt_pk_bf16_f32 v93, v96, v97
	v_cvt_pk_bf16_f32 v94, v94, v95
	v_cvt_pk_bf16_f32 v95, v100, v101
	v_lshl_add_u64 v[90:91], v[90:91], 0, v[108:109]
	global_store_dwordx4 v[90:91], v[92:95], off
	s_nop 1
	v_mov_b32_e32 v92, v196
	s_waitcnt lgkmcnt(0)
	v_pk_mul_f32 v[88:89], v[88:89], v[92:93] op_sel_hi:[1,0]
	v_pk_mul_f32 v[86:87], v[86:87], v[92:93] op_sel_hi:[1,0]
	v_pk_fma_f32 v[88:89], v[182:183], v[88:89], v[32:33]
	v_pk_mul_f32 v[94:95], v[124:125], v[92:93] op_sel_hi:[1,0]
	v_pk_mul_f32 v[92:93], v[122:123], v[92:93] op_sel_hi:[1,0]
	v_pk_fma_f32 v[96:97], v[188:189], v[94:95], v[28:29]
	v_pk_fma_f32 v[94:95], v[190:191], v[92:93], v[26:27]
	v_cvt_pk_bf16_f32 v93, v88, v89
	s_nop 1
	v_mov_b32_e32 v88, v197
	v_pk_fma_f32 v[86:87], v[186:187], v[86:87], v[30:31]
	v_cvt_pk_bf16_f32 v94, v94, v95
	v_cvt_pk_bf16_f32 v92, v86, v87
	v_lshlrev_b64 v[86:87], 11, v[152:153]
	v_lshl_add_u64 v[86:87], s[74:75], 0, v[86:87]
	v_cvt_pk_bf16_f32 v95, v96, v97
	v_lshl_add_u64 v[86:87], v[86:87], 0, v[108:109]
	s_waitcnt lgkmcnt(0)
; __device__ __forceinline__ unsigned pk2(float lo, float hi) { f32x2 v = {lo, hi}; bf16x2_t b = __builtin_convertvector(v, bf16x2_t); return __builtin_bit_cast(unsigned, b); }
;     __device__ __forceinline__ void operator()(f32x4 (&acc)[2][2][4][2], const Unit& u, int wr, int wc, int fr, int fq) const {
;     ...
; #pragma unroll
;         for (int bj = 0; bj < 2; ++bj) {
;             const int col = u.pn * BM + bj * HALF + wc * 32 + 8 * fq;
;             f32x4 mp[2], sh[2];
; #pragma unroll
;             for (int n = 0; n < 2; ++n) { mp[n] = *(const f32x4*)(gpre + col + 4 * n) * (*(const f32x4*)(md + sc_off + col + 4 * n) + 1.0f); sh[n] = *(const f32x4*)(md + sh_off + col + 4 * n); }
; #pragma unroll
;             for (int ai = 0; ai < 2; ++ai)
; #pragma unroll
;                 for (int m = 0; m < 4; ++m) {
;                     const int rl = ai * HALF + wr * 64 + m * 16 + fr; const float r = S[rl];
;                     const f32x4 h0 = (acc[ai][bj][m][0] * r) * mp[0] + sh[0], h1 = (acc[ai][bj][m][1] * r) * mp[1] + sh[1];
;                     u32x4 w; w.x = pk2(h0[0], h0[1]); w.y = pk2(h0[2], h0[3]); w.z = pk2(h1[0], h1[1]); w.w = pk2(h1[2], h1[3]);
;                     *(u32x4*)(XN + (size_t)(u.pm * BM + rl) * DM + col) = w;
;                 }
	v_pk_mul_f32 v[84:85], v[84:85], v[88:89] op_sel_hi:[1,0]
	global_store_dwordx4 v[86:87], v[92:95], off
	v_pk_fma_f32 v[84:85], v[182:183], v[84:85], v[32:33]
	v_pk_mul_f32 v[82:83], v[82:83], v[88:89] op_sel_hi:[1,0]
	v_pk_mul_f32 v[92:93], v[120:121], v[88:89] op_sel_hi:[1,0]
	v_pk_fma_f32 v[82:83], v[186:187], v[82:83], v[30:31]
	v_pk_fma_f32 v[96:97], v[188:189], v[92:93], v[28:29]
	v_cvt_pk_bf16_f32 v93, v84, v85
	s_nop 1
	v_mov_b32_e32 v84, v198
	v_pk_mul_f32 v[88:89], v[118:119], v[88:89] op_sel_hi:[1,0]
	v_cvt_pk_bf16_f32 v92, v82, v83
	v_pk_fma_f32 v[88:89], v[190:191], v[88:89], v[26:27]
	v_lshlrev_b64 v[82:83], 11, v[158:159]
	s_waitcnt lgkmcnt(0)
	v_pk_mul_f32 v[78:79], v[78:79], v[84:85] op_sel_hi:[1,0]
	v_pk_mul_f32 v[72:73], v[72:73], v[84:85] op_sel_hi:[1,0]
	v_pk_fma_f32 v[78:79], v[186:187], v[78:79], v[30:31]
	v_pk_mul_f32 v[70:71], v[70:71], v[84:85] op_sel_hi:[1,0]
	v_pk_mul_f32 v[80:81], v[80:81], v[84:85] op_sel_hi:[1,0]
	v_pk_fma_f32 v[84:85], v[188:189], v[72:73], v[28:29]
	v_pk_fma_f32 v[72:73], v[190:191], v[70:71], v[26:27]
	v_cvt_pk_bf16_f32 v70, v78, v79
	v_lshlrev_b64 v[78:79], 11, v[156:157]
	v_pk_fma_f32 v[80:81], v[182:183], v[80:81], v[32:33]
	v_lshl_add_u64 v[78:79], s[74:75], 0, v[78:79]
	v_cvt_pk_bf16_f32 v71, v80, v81
	v_cvt_pk_bf16_f32 v72, v72, v73
	v_cvt_pk_bf16_f32 v73, v84, v85
	v_lshl_add_u64 v[78:79], v[78:79], 0, v[108:109]
	global_store_dwordx4 v[78:79], v[70:73], off
	s_nop 1
	v_mov_b32_e32 v70, v199
	v_lshl_add_u64 v[82:83], s[74:75], 0, v[82:83]
	v_cvt_pk_bf16_f32 v94, v88, v89
	v_cvt_pk_bf16_f32 v95, v96, v97
	v_lshl_add_u64 v[82:83], v[82:83], 0, v[108:109]
	s_waitcnt lgkmcnt(0)
	v_pk_mul_f32 v[74:75], v[74:75], v[70:71] op_sel_hi:[1,0]
	v_pk_mul_f32 v[68:69], v[68:69], v[70:71] op_sel_hi:[1,0]
	v_pk_fma_f32 v[30:31], v[186:187], v[74:75], v[30:31]
	v_pk_mul_f32 v[66:67], v[66:67], v[70:71] op_sel_hi:[1,0]
	v_pk_mul_f32 v[72:73], v[76:77], v[70:71] op_sel_hi:[1,0]
	v_pk_fma_f32 v[68:69], v[188:189], v[68:69], v[28:29]
	v_pk_fma_f32 v[28:29], v[190:191], v[66:67], v[26:27]
	v_cvt_pk_bf16_f32 v26, v30, v31
	v_lshlrev_b64 v[30:31], 11, v[154:155]
	v_pk_fma_f32 v[32:33], v[182:183], v[72:73], v[32:33]
	v_lshl_add_u64 v[30:31], s[74:75], 0, v[30:31]
	v_cvt_pk_bf16_f32 v27, v32, v33
	v_cvt_pk_bf16_f32 v28, v28, v29
	v_cvt_pk_bf16_f32 v29, v68, v69
	v_lshl_add_u64 v[66:67], v[30:31], 0, v[108:109]
	global_store_dwordx4 v[82:83], v[92:95], off
	global_store_dwordx4 v[66:67], v[26:29], off
	s_nop 1
	v_lshlrev_b64 v[26:27], 2, v[222:223]
	v_lshl_add_u64 v[72:73], s[8:9], 0, v[26:27]
	v_lshl_add_u64 v[80:81], s[40:41], 0, v[26:27]
	global_load_dwordx4 v[74:77], v[184:185], off offset:528
	global_load_dwordx4 v[26:29], v[184:185], off offset:512
	global_load_dwordx4 v[30:33], v[72:73], off
	s_waitcnt vmcnt(0)
	v_pk_add_f32 v[32:33], v[32:33], 1.0 op_sel_hi:[1,0]
	v_pk_add_f32 v[30:31], v[30:31], 1.0 op_sel_hi:[1,0]
	v_pk_mul_f32 v[68:69], v[28:29], v[32:33]
	v_pk_mul_f32 v[70:71], v[26:27], v[30:31]
	global_load_dwordx4 v[26:29], v[80:81], off offset:16
	global_load_dwordx4 v[30:33], v[80:81], off
	global_load_dwordx4 v[92:95], v[72:73], off offset:16
	s_waitcnt vmcnt(0)
	v_pk_add_f32 v[72:73], v[94:95], 1.0 op_sel_hi:[1,0]
	s_nop 0
	v_pk_mul_f32 v[72:73], v[76:77], v[72:73]
	s_nop 1
	v_mov_b32_e32 v76, v192
	v_pk_add_f32 v[80:81], v[92:93], 1.0 op_sel_hi:[1,0]
	s_waitcnt lgkmcnt(0)
	v_pk_mul_f32 v[64:65], v[64:65], v[76:77] op_sel_hi:[1,0]
	v_pk_mul_f32 v[74:75], v[74:75], v[80:81]
	v_pk_mul_f32 v[62:63], v[62:63], v[76:77] op_sel_hi:[1,0]
	v_pk_mul_f32 v[80:81], v[136:137], v[76:77] op_sel_hi:[1,0]
	v_pk_mul_f32 v[76:77], v[134:135], v[76:77] op_sel_hi:[1,0]
	v_pk_fma_f32 v[64:65], v[68:69], v[64:65], v[32:33]
	v_pk_fma_f32 v[62:63], v[70:71], v[62:63], v[30:31]
	v_pk_fma_f32 v[80:81], v[72:73], v[80:81], v[28:29]
	v_pk_fma_f32 v[76:77], v[74:75], v[76:77], v[26:27]
	v_cvt_pk_bf16_f32 v62, v62, v63
	v_cvt_pk_bf16_f32 v63, v64, v65
	v_cvt_pk_bf16_f32 v64, v76, v77
	v_cvt_pk_bf16_f32 v65, v80, v81
	global_store_dwordx4 v[106:107], v[62:65], off offset:256
	s_nop 1
	v_mov_b32_e32 v62, v193
	s_waitcnt lgkmcnt(0)
; __device__ __forceinline__ unsigned pk2(float lo, float hi) { f32x2 v = {lo, hi}; bf16x2_t b = __builtin_convertvector(v, bf16x2_t); return __builtin_bit_cast(unsigned, b); }
;     __device__ __forceinline__ void operator()(f32x4 (&acc)[2][2][4][2], const Unit& u, int wr, int wc, int fr, int fq) const {
;     ...
; #pragma unroll
;             for (int ai = 0; ai < 2; ++ai)
; #pragma unroll
;                 for (int m = 0; m < 4; ++m) {
;                     const int rl = ai * HALF + wr * 64 + m * 16 + fr; const float r = S[rl];
;                     const f32x4 h0 = (acc[ai][bj][m][0] * r) * mp[0] + sh[0], h1 = (acc[ai][bj][m][1] * r) * mp[1] + sh[1];
;                     u32x4 w; w.x = pk2(h0[0], h0[1]); w.y = pk2(h0[2], h0[3]); w.z = pk2(h1[0], h1[1]); w.w = pk2(h1[2], h1[3]);
;                     *(u32x4*)(XN + (size_t)(u.pm * BM + rl) * DM + col) = w;
;                 }
	v_pk_mul_f32 v[60:61], v[60:61], v[62:63] op_sel_hi:[1,0]
	v_pk_mul_f32 v[58:59], v[58:59], v[62:63] op_sel_hi:[1,0]
	v_pk_mul_f32 v[64:65], v[132:133], v[62:63] op_sel_hi:[1,0]
	v_pk_mul_f32 v[62:63], v[130:131], v[62:63] op_sel_hi:[1,0]
	v_pk_fma_f32 v[60:61], v[68:69], v[60:61], v[32:33]
	v_pk_fma_f32 v[58:59], v[70:71], v[58:59], v[30:31]
	v_pk_fma_f32 v[64:65], v[72:73], v[64:65], v[28:29]
	v_pk_fma_f32 v[62:63], v[74:75], v[62:63], v[26:27]
	v_cvt_pk_bf16_f32 v58, v58, v59
	v_cvt_pk_bf16_f32 v59, v60, v61
	v_cvt_pk_bf16_f32 v60, v62, v63
	v_cvt_pk_bf16_f32 v61, v64, v65
	global_store_dwordx4 v[110:111], v[58:61], off offset:256
	s_nop 1
	v_mov_b32_e32 v58, v194
	s_waitcnt lgkmcnt(0)
	v_pk_mul_f32 v[56:57], v[56:57], v[58:59] op_sel_hi:[1,0]
	v_pk_mul_f32 v[54:55], v[54:55], v[58:59] op_sel_hi:[1,0]
	v_pk_mul_f32 v[36:37], v[36:37], v[58:59] op_sel_hi:[1,0]
	v_pk_mul_f32 v[34:35], v[34:35], v[58:59] op_sel_hi:[1,0]
	v_pk_fma_f32 v[56:57], v[68:69], v[56:57], v[32:33]
	v_pk_fma_f32 v[54:55], v[70:71], v[54:55], v[30:31]
	v_pk_fma_f32 v[58:59], v[72:73], v[36:37], v[28:29]
	v_pk_fma_f32 v[36:37], v[74:75], v[34:35], v[26:27]
	v_cvt_pk_bf16_f32 v34, v54, v55
	v_cvt_pk_bf16_f32 v35, v56, v57
	v_cvt_pk_bf16_f32 v36, v36, v37
	v_cvt_pk_bf16_f32 v37, v58, v59
	global_store_dwordx4 v[98:99], v[34:37], off offset:256
	s_nop 1
	v_mov_b32_e32 v34, v195
	s_waitcnt lgkmcnt(0)
	v_pk_mul_f32 v[50:51], v[50:51], v[34:35] op_sel_hi:[1,0]
	v_pk_mul_f32 v[36:37], v[52:53], v[34:35] op_sel_hi:[1,0]
	v_pk_mul_f32 v[24:25], v[24:25], v[34:35] op_sel_hi:[1,0]
	v_pk_mul_f32 v[22:23], v[22:23], v[34:35] op_sel_hi:[1,0]
	v_pk_fma_f32 v[36:37], v[68:69], v[36:37], v[32:33]
	v_pk_fma_f32 v[50:51], v[70:71], v[50:51], v[30:31]
	v_pk_fma_f32 v[34:35], v[72:73], v[24:25], v[28:29]
	v_pk_fma_f32 v[24:25], v[74:75], v[22:23], v[26:27]
	v_cvt_pk_bf16_f32 v22, v50, v51
	v_cvt_pk_bf16_f32 v23, v36, v37
	v_cvt_pk_bf16_f32 v24, v24, v25
	v_cvt_pk_bf16_f32 v25, v34, v35
	global_store_dwordx4 v[90:91], v[22:25], off offset:256
	s_nop 1
	v_mov_b32_e32 v22, v196
	s_waitcnt lgkmcnt(0)
	v_pk_mul_f32 v[34:35], v[46:47], v[22:23] op_sel_hi:[1,0]
	v_pk_mul_f32 v[24:25], v[48:49], v[22:23] op_sel_hi:[1,0]
	v_pk_mul_f32 v[16:17], v[16:17], v[22:23] op_sel_hi:[1,0]
	v_pk_mul_f32 v[14:15], v[14:15], v[22:23] op_sel_hi:[1,0]
	v_pk_fma_f32 v[24:25], v[68:69], v[24:25], v[32:33]
	v_pk_fma_f32 v[34:35], v[70:71], v[34:35], v[30:31]
	v_pk_fma_f32 v[22:23], v[72:73], v[16:17], v[28:29]
	v_pk_fma_f32 v[16:17], v[74:75], v[14:15], v[26:27]
	v_cvt_pk_bf16_f32 v14, v34, v35
	v_cvt_pk_bf16_f32 v15, v24, v25
	v_cvt_pk_bf16_f32 v16, v16, v17
	v_cvt_pk_bf16_f32 v17, v22, v23
	global_store_dwordx4 v[86:87], v[14:17], off offset:256
	s_nop 1
	v_mov_b32_e32 v14, v197
	s_waitcnt lgkmcnt(0)
	v_pk_mul_f32 v[22:23], v[42:43], v[14:15] op_sel_hi:[1,0]
	v_pk_mul_f32 v[16:17], v[44:45], v[14:15] op_sel_hi:[1,0]
	v_pk_mul_f32 v[10:11], v[10:11], v[14:15] op_sel_hi:[1,0]
	v_pk_mul_f32 v[8:9], v[8:9], v[14:15] op_sel_hi:[1,0]
	v_pk_fma_f32 v[16:17], v[68:69], v[16:17], v[32:33]
	v_pk_fma_f32 v[22:23], v[70:71], v[22:23], v[30:31]
	v_pk_fma_f32 v[14:15], v[72:73], v[10:11], v[28:29]
	v_pk_fma_f32 v[10:11], v[74:75], v[8:9], v[26:27]
	v_cvt_pk_bf16_f32 v8, v22, v23
	v_cvt_pk_bf16_f32 v9, v16, v17
	v_cvt_pk_bf16_f32 v10, v10, v11
	v_cvt_pk_bf16_f32 v11, v14, v15
	global_store_dwordx4 v[82:83], v[8:11], off offset:256
	s_nop 1
	v_mov_b32_e32 v8, v198
	s_waitcnt lgkmcnt(0)
	v_pk_mul_f32 v[14:15], v[38:39], v[8:9] op_sel_hi:[1,0]
	v_pk_mul_f32 v[10:11], v[40:41], v[8:9] op_sel_hi:[1,0]
	v_pk_mul_f32 v[6:7], v[6:7], v[8:9] op_sel_hi:[1,0]
	v_pk_mul_f32 v[4:5], v[4:5], v[8:9] op_sel_hi:[1,0]
	v_pk_fma_f32 v[10:11], v[68:69], v[10:11], v[32:33]
	v_pk_fma_f32 v[14:15], v[70:71], v[14:15], v[30:31]
	v_pk_fma_f32 v[8:9], v[72:73], v[6:7], v[28:29]
	v_pk_fma_f32 v[6:7], v[74:75], v[4:5], v[26:27]
	v_cvt_pk_bf16_f32 v4, v14, v15
	v_cvt_pk_bf16_f32 v5, v10, v11
	v_cvt_pk_bf16_f32 v6, v6, v7
	v_cvt_pk_bf16_f32 v7, v8, v9
	global_store_dwordx4 v[78:79], v[4:7], off offset:256
	s_nop 1
	v_mov_b32_e32 v4, v199
	s_waitcnt lgkmcnt(0)
	v_pk_mul_f32 v[8:9], v[18:19], v[4:5] op_sel_hi:[1,0]
	v_pk_mul_f32 v[6:7], v[20:21], v[4:5] op_sel_hi:[1,0]
	v_pk_mul_f32 v[2:3], v[2:3], v[4:5] op_sel_hi:[1,0]
	v_pk_mul_f32 v[0:1], v[0:1], v[4:5] op_sel_hi:[1,0]
	v_pk_fma_f32 v[6:7], v[68:69], v[6:7], v[32:33]
	v_pk_fma_f32 v[8:9], v[70:71], v[8:9], v[30:31]
	v_pk_fma_f32 v[4:5], v[72:73], v[2:3], v[28:29]
	v_pk_fma_f32 v[2:3], v[74:75], v[0:1], v[26:27]
	v_cvt_pk_bf16_f32 v0, v8, v9
	v_cvt_pk_bf16_f32 v1, v6, v7
	v_cvt_pk_bf16_f32 v2, v2, v3
	v_cvt_pk_bf16_f32 v3, v4, v5
	global_store_dwordx4 v[66:67], v[0:3], off offset:256

; __device__ __forceinline__ unsigned pk2(float lo, float hi) { f32x2 v = {lo, hi}; bf16x2_t b = __builtin_convertvector(v, bf16x2_t); return __builtin_bit_cast(unsigned, b); }
;     __device__ __forceinline__ void operator()(f32x4 (&acc)[2][2][4][2], const Unit& u, int wr, int wc, int fr, int fq) const {
;     ...
; #pragma unroll
;         for (int bj = 0; bj < 2; ++bj) {
;             const int col = u.pn * BM + bj * HALF + wc * 32 + 8 * fq;
;             f32x4 mp[2], sh[2];
; #pragma unroll
;             for (int n = 0; n < 2; ++n) { mp[n] = *(const f32x4*)(gpre + col + 4 * n) * (*(const f32x4*)(md + sc_off + col + 4 * n) + 1.0f); sh[n] = *(const f32x4*)(md + sh_off + col + 4 * n); }
; #pragma unroll
;             for (int ai = 0; ai < 2; ++ai)
; #pragma unroll
;                 for (int m = 0; m < 4; ++m) {
;                     const int rl = ai * HALF + wr * 64 + m * 16 + fr; const float r = S[rl];
;                     const f32x4 h0 = (acc[ai][bj][m][0] * r) * mp[0] + sh[0], h1 = (acc[ai][bj][m][1] * r) * mp[1] + sh[1];
;                     u32x4 w; w.x = pk2(h0[0], h0[1]); w.y = pk2(h0[2], h0[3]); w.z = pk2(h1[0], h1[1]); w.w = pk2(h1[2], h1[3]);
;                     *(u32x4*)(XN + (size_t)(u.pm * BM + rl) * DM + col) = w;
;                 }
.LBB0_1250:
	s_or_b64 exec, exec, s[6:7]
	s_add_u32 s8, s49, s92
	s_addc_u32 s9, s50, s93
	s_add_u32 s6, s8, 0x1000
	s_addc_u32 s7, s9, 0
	s_waitcnt vmcnt(0) lgkmcnt(0)
	s_barrier
	ds_read_b32 v169, v246
	ds_read_b32 v176, v247
	ds_read_b32 v177, v248
	ds_read_b32 v198, v249
	ds_read_b32 v199, v250
	ds_read_b32 v200, v251
	ds_read_b32 v201, v236
	ds_read_b32 v202, v166
	s_waitcnt lgkmcnt(0)
	v_lshl_add_u64 v[138:139], s[22:23], 0, v[194:195]
	v_lshl_add_u64 v[30:31], s[6:7], 0, v[194:195]
	global_load_dwordx4 v[170:173], v[138:139], off offset:16
	s_waitcnt lgkmcnt(0)
	global_load_dwordx4 v[26:29], v[138:139], off
	global_load_dwordx4 v[146:149], v[30:31], off offset:16
	s_nop 0
	global_load_dwordx4 v[30:33], v[30:31], off
	v_lshl_add_u64 v[140:141], s[8:9], 0, v[194:195]
	s_waitcnt vmcnt(1)
	v_pk_add_f32 v[148:149], v[148:149], 1.0 op_sel_hi:[1,0]
	s_waitcnt vmcnt(0)
	v_pk_add_f32 v[32:33], v[32:33], 1.0 op_sel_hi:[1,0]
	v_pk_add_f32 v[30:31], v[30:31], 1.0 op_sel_hi:[1,0]
	v_pk_mul_f32 v[142:143], v[28:29], v[32:33]
	v_pk_mul_f32 v[144:145], v[26:27], v[30:31]
	global_load_dwordx4 v[26:29], v[140:141], off offset:16
	global_load_dwordx4 v[30:33], v[140:141], off
	v_pk_add_f32 v[174:175], v[146:147], 1.0 op_sel_hi:[1,0]
	v_pk_mul_f32 v[146:147], v[172:173], v[148:149]
	v_pk_mul_f32 v[148:149], v[170:171], v[174:175]
	s_nop 1
	v_mov_b32_e32 v170, v169
	s_waitcnt lgkmcnt(0)
	v_pk_mul_f32 v[78:79], v[78:79], v[170:171] op_sel_hi:[1,0]
	v_pk_mul_f32 v[80:81], v[80:81], v[170:171] op_sel_hi:[1,0]
	v_pk_mul_f32 v[108:109], v[108:109], v[170:171] op_sel_hi:[1,0]
	v_pk_mul_f32 v[106:107], v[106:107], v[170:171] op_sel_hi:[1,0]
	s_waitcnt vmcnt(1)
	v_pk_fma_f32 v[170:171], v[146:147], v[108:109], v[28:29]
	s_waitcnt vmcnt(0)
	v_pk_fma_f32 v[78:79], v[144:145], v[78:79], v[30:31]
	v_pk_fma_f32 v[80:81], v[142:143], v[80:81], v[32:33]
	v_pk_fma_f32 v[108:109], v[148:149], v[106:107], v[26:27]
	v_cvt_pk_bf16_f32 v106, v78, v79
	v_lshlrev_b64 v[78:79], 11, v[192:193]
	v_cvt_pk_bf16_f32 v107, v80, v81
	v_lshl_add_u64 v[78:79], s[12:13], 0, v[78:79]
	v_lshlrev_b64 v[80:81], 1, v[184:185]
	v_cvt_pk_bf16_f32 v108, v108, v109
	v_cvt_pk_bf16_f32 v109, v170, v171
	v_lshl_add_u64 v[78:79], v[78:79], 0, v[80:81]
	global_store_dwordx4 v[78:79], v[106:109], off
	s_nop 1
	v_mov_b32_e32 v106, v176
	s_waitcnt lgkmcnt(0)
	v_pk_mul_f32 v[76:77], v[76:77], v[106:107] op_sel_hi:[1,0]
	v_pk_mul_f32 v[74:75], v[74:75], v[106:107] op_sel_hi:[1,0]
	v_pk_mul_f32 v[98:99], v[98:99], v[106:107] op_sel_hi:[1,0]
	v_pk_fma_f32 v[76:77], v[142:143], v[76:77], v[32:33]
	v_pk_fma_f32 v[74:75], v[144:145], v[74:75], v[30:31]
	v_pk_fma_f32 v[98:99], v[148:149], v[98:99], v[26:27]
	v_pk_mul_f32 v[100:101], v[100:101], v[106:107] op_sel_hi:[1,0]
	v_cvt_pk_bf16_f32 v74, v74, v75
	v_cvt_pk_bf16_f32 v75, v76, v77
	v_cvt_pk_bf16_f32 v76, v98, v99
	v_lshlrev_b64 v[98:99], 11, v[190:191]
	v_pk_fma_f32 v[100:101], v[146:147], v[100:101], v[28:29]
	v_lshl_add_u64 v[98:99], s[12:13], 0, v[98:99]
	v_cvt_pk_bf16_f32 v77, v100, v101
	v_lshl_add_u64 v[98:99], v[98:99], 0, v[80:81]
	global_store_dwordx4 v[98:99], v[74:77], off
	s_nop 1
	v_mov_b32_e32 v74, v177
	s_waitcnt lgkmcnt(0)
	v_pk_mul_f32 v[72:73], v[72:73], v[74:75] op_sel_hi:[1,0]
	v_pk_mul_f32 v[70:71], v[70:71], v[74:75] op_sel_hi:[1,0]
	v_pk_mul_f32 v[76:77], v[88:89], v[74:75] op_sel_hi:[1,0]
	v_pk_mul_f32 v[74:75], v[86:87], v[74:75] op_sel_hi:[1,0]
	v_pk_fma_f32 v[72:73], v[142:143], v[72:73], v[32:33]
	v_pk_fma_f32 v[70:71], v[144:145], v[70:71], v[30:31]
	v_pk_fma_f32 v[74:75], v[148:149], v[74:75], v[26:27]
	v_cvt_pk_bf16_f32 v70, v70, v71
	v_cvt_pk_bf16_f32 v71, v72, v73
	v_cvt_pk_bf16_f32 v72, v74, v75
	v_lshlrev_b64 v[74:75], 11, v[178:179]
	v_pk_fma_f32 v[76:77], v[146:147], v[76:77], v[28:29]
	v_lshl_add_u64 v[74:75], s[12:13], 0, v[74:75]
	v_cvt_pk_bf16_f32 v73, v76, v77
	v_lshl_add_u64 v[74:75], v[74:75], 0, v[80:81]
	global_store_dwordx4 v[74:75], v[70:73], off
	s_nop 1
	v_mov_b32_e32 v70, v198
	s_waitcnt lgkmcnt(0)
	v_pk_mul_f32 v[64:65], v[64:65], v[70:71] op_sel_hi:[1,0]
	v_pk_mul_f32 v[62:63], v[62:63], v[70:71] op_sel_hi:[1,0]
	v_pk_fma_f32 v[64:65], v[142:143], v[64:65], v[32:33]
	v_pk_mul_f32 v[72:73], v[124:125], v[70:71] op_sel_hi:[1,0]
	v_pk_mul_f32 v[70:71], v[122:123], v[70:71] op_sel_hi:[1,0]
	v_pk_fma_f32 v[76:77], v[146:147], v[72:73], v[28:29]
	v_pk_fma_f32 v[72:73], v[148:149], v[70:71], v[26:27]
	v_cvt_pk_bf16_f32 v71, v64, v65
	s_nop 1
	v_mov_b32_e32 v64, v199
	v_pk_fma_f32 v[62:63], v[144:145], v[62:63], v[30:31]
	v_cvt_pk_bf16_f32 v72, v72, v73
	v_cvt_pk_bf16_f32 v70, v62, v63
	v_lshlrev_b64 v[62:63], 11, v[186:187]
	v_lshl_add_u64 v[62:63], s[12:13], 0, v[62:63]
	v_cvt_pk_bf16_f32 v73, v76, v77
	v_lshl_add_u64 v[62:63], v[62:63], 0, v[80:81]
	s_waitcnt lgkmcnt(0)
	v_pk_mul_f32 v[60:61], v[60:61], v[64:65] op_sel_hi:[1,0]
	global_store_dwordx4 v[62:63], v[70:73], off
	v_pk_fma_f32 v[60:61], v[142:143], v[60:61], v[32:33]
	v_pk_mul_f32 v[58:59], v[58:59], v[64:65] op_sel_hi:[1,0]
	v_pk_mul_f32 v[70:71], v[120:121], v[64:65] op_sel_hi:[1,0]
	v_pk_fma_f32 v[58:59], v[144:145], v[58:59], v[30:31]
	v_pk_fma_f32 v[76:77], v[146:147], v[70:71], v[28:29]
	v_cvt_pk_bf16_f32 v71, v60, v61
	s_nop 1
	v_mov_b32_e32 v60, v200
	v_pk_mul_f32 v[64:65], v[118:119], v[64:65] op_sel_hi:[1,0]
	v_cvt_pk_bf16_f32 v70, v58, v59
	v_lshlrev_b64 v[58:59], 11, v[164:165]
	v_pk_fma_f32 v[64:65], v[148:149], v[64:65], v[26:27]
	v_lshl_add_u64 v[58:59], s[12:13], 0, v[58:59]
	s_waitcnt lgkmcnt(0)
; __device__ __forceinline__ unsigned pk2(float lo, float hi) { f32x2 v = {lo, hi}; bf16x2_t b = __builtin_convertvector(v, bf16x2_t); return __builtin_bit_cast(unsigned, b); }
;     __device__ __forceinline__ void operator()(f32x4 (&acc)[2][2][4][2], const Unit& u, int wr, int wc, int fr, int fq) const {
;     ...
; #pragma unroll
;         for (int bj = 0; bj < 2; ++bj) {
;             const int col = u.pn * BM + bj * HALF + wc * 32 + 8 * fq;
;             f32x4 mp[2], sh[2];
; #pragma unroll
;             for (int n = 0; n < 2; ++n) { mp[n] = *(const f32x4*)(gpre + col + 4 * n) * (*(const f32x4*)(md + sc_off + col + 4 * n) + 1.0f); sh[n] = *(const f32x4*)(md + sh_off + col + 4 * n); }
; #pragma unroll
;             for (int ai = 0; ai < 2; ++ai)
; #pragma unroll
;                 for (int m = 0; m < 4; ++m) {
;                     const int rl = ai * HALF + wr * 64 + m * 16 + fr; const float r = S[rl];
;                     const f32x4 h0 = (acc[ai][bj][m][0] * r) * mp[0] + sh[0], h1 = (acc[ai][bj][m][1] * r) * mp[1] + sh[1];
;                     u32x4 w; w.x = pk2(h0[0], h0[1]); w.y = pk2(h0[2], h0[3]); w.z = pk2(h1[0], h1[1]); w.w = pk2(h1[2], h1[3]);
;                     *(u32x4*)(XN + (size_t)(u.pm * BM + rl) * DM + col) = w;
;                 }
	v_pk_mul_f32 v[54:55], v[54:55], v[60:61] op_sel_hi:[1,0]
	v_cvt_pk_bf16_f32 v72, v64, v65
	v_cvt_pk_bf16_f32 v73, v76, v77
	v_lshl_add_u64 v[58:59], v[58:59], 0, v[80:81]
	v_pk_fma_f32 v[54:55], v[144:145], v[54:55], v[30:31]
	global_store_dwordx4 v[58:59], v[70:73], off
	v_pk_mul_f32 v[56:57], v[56:57], v[60:61] op_sel_hi:[1,0]
	v_pk_mul_f32 v[64:65], v[128:129], v[60:61] op_sel_hi:[1,0]
	v_cvt_pk_bf16_f32 v70, v54, v55
	v_lshlrev_b64 v[54:55], 11, v[188:189]
	v_pk_fma_f32 v[56:57], v[142:143], v[56:57], v[32:33]
	v_lshl_add_u64 v[54:55], s[12:13], 0, v[54:55]
	v_cvt_pk_bf16_f32 v71, v56, v57
	v_lshl_add_u64 v[56:57], v[54:55], 0, v[80:81]
	s_nop 1
	v_mov_b32_e32 v54, v201
	v_pk_mul_f32 v[60:61], v[126:127], v[60:61] op_sel_hi:[1,0]
	v_pk_fma_f32 v[64:65], v[146:147], v[64:65], v[28:29]
	v_pk_fma_f32 v[60:61], v[148:149], v[60:61], v[26:27]
	v_cvt_pk_bf16_f32 v73, v64, v65
	v_cvt_pk_bf16_f32 v72, v60, v61
	s_waitcnt lgkmcnt(0)
	v_pk_mul_f32 v[52:53], v[52:53], v[54:55] op_sel_hi:[1,0]
	v_pk_mul_f32 v[50:51], v[50:51], v[54:55] op_sel_hi:[1,0]
	v_pk_mul_f32 v[60:61], v[116:117], v[54:55] op_sel_hi:[1,0]
	v_pk_mul_f32 v[54:55], v[114:115], v[54:55] op_sel_hi:[1,0]
	v_pk_fma_f32 v[52:53], v[142:143], v[52:53], v[32:33]
	v_pk_fma_f32 v[50:51], v[144:145], v[50:51], v[30:31]
	v_pk_fma_f32 v[54:55], v[148:149], v[54:55], v[26:27]
	v_cvt_pk_bf16_f32 v50, v50, v51
	v_cvt_pk_bf16_f32 v51, v52, v53
	v_cvt_pk_bf16_f32 v52, v54, v55
	v_lshlrev_b64 v[54:55], 11, v[182:183]
	v_pk_fma_f32 v[60:61], v[146:147], v[60:61], v[28:29]
	v_lshl_add_u64 v[54:55], s[12:13], 0, v[54:55]
	v_cvt_pk_bf16_f32 v53, v60, v61
	v_lshl_add_u64 v[60:61], v[54:55], 0, v[80:81]
	global_store_dwordx4 v[60:61], v[50:53], off
	s_nop 1
	v_mov_b32_e32 v50, v202
	global_store_dwordx4 v[56:57], v[70:73], off
	s_waitcnt lgkmcnt(0)
	v_pk_mul_f32 v[48:49], v[48:49], v[50:51] op_sel_hi:[1,0]
	v_pk_mul_f32 v[46:47], v[46:47], v[50:51] op_sel_hi:[1,0]
	v_pk_fma_f32 v[32:33], v[142:143], v[48:49], v[32:33]
	v_pk_fma_f32 v[30:31], v[144:145], v[46:47], v[30:31]
	v_pk_mul_f32 v[46:47], v[112:113], v[50:51] op_sel_hi:[1,0]
	v_pk_mul_f32 v[48:49], v[110:111], v[50:51] op_sel_hi:[1,0]
	v_pk_fma_f32 v[46:47], v[146:147], v[46:47], v[28:29]
	v_pk_fma_f32 v[28:29], v[148:149], v[48:49], v[26:27]
	v_cvt_pk_bf16_f32 v26, v30, v31
	v_lshlrev_b64 v[30:31], 11, v[180:181]
	v_lshl_add_u64 v[30:31], s[12:13], 0, v[30:31]
	v_cvt_pk_bf16_f32 v27, v32, v33
	v_cvt_pk_bf16_f32 v28, v28, v29
	v_cvt_pk_bf16_f32 v29, v46, v47
	v_lshl_add_u64 v[46:47], v[30:31], 0, v[80:81]
	global_store_dwordx4 v[46:47], v[26:29], off
	v_lshl_add_u64 v[30:31], v[196:197], 2, s[6:7]
	global_load_dwordx4 v[70:73], v[138:139], off offset:528
	global_load_dwordx4 v[26:29], v[138:139], off offset:512
	global_load_dwordx4 v[52:55], v[30:31], off offset:16
	s_nop 0
	global_load_dwordx4 v[30:33], v[30:31], off
	s_waitcnt vmcnt(1)
	v_pk_add_f32 v[54:55], v[54:55], 1.0 op_sel_hi:[1,0]
	s_waitcnt vmcnt(0)
	v_pk_add_f32 v[32:33], v[32:33], 1.0 op_sel_hi:[1,0]
	v_pk_add_f32 v[30:31], v[30:31], 1.0 op_sel_hi:[1,0]
	v_pk_mul_f32 v[48:49], v[28:29], v[32:33]
	v_pk_mul_f32 v[50:51], v[26:27], v[30:31]
	global_load_dwordx4 v[26:29], v[140:141], off offset:528
	global_load_dwordx4 v[30:33], v[140:141], off offset:512
	v_pk_add_f32 v[64:65], v[52:53], 1.0 op_sel_hi:[1,0]
	v_pk_mul_f32 v[52:53], v[72:73], v[54:55]
	v_pk_mul_f32 v[54:55], v[70:71], v[64:65]
	s_nop 1
	v_mov_b32_e32 v64, v169
	s_waitcnt lgkmcnt(0)
	v_pk_mul_f32 v[70:71], v[104:105], v[64:65] op_sel_hi:[1,0]
	v_pk_mul_f32 v[72:73], v[102:103], v[64:65] op_sel_hi:[1,0]
	v_pk_mul_f32 v[36:37], v[36:37], v[64:65] op_sel_hi:[1,0]
	v_pk_mul_f32 v[34:35], v[34:35], v[64:65] op_sel_hi:[1,0]
	s_waitcnt vmcnt(1)
	v_pk_fma_f32 v[64:65], v[52:53], v[36:37], v[28:29]
	s_waitcnt vmcnt(0)
	v_pk_fma_f32 v[70:71], v[48:49], v[70:71], v[32:33]
	v_pk_fma_f32 v[72:73], v[50:51], v[72:73], v[30:31]
	v_pk_fma_f32 v[36:37], v[54:55], v[34:35], v[26:27]
	v_cvt_pk_bf16_f32 v34, v72, v73
	v_cvt_pk_bf16_f32 v35, v70, v71
	v_cvt_pk_bf16_f32 v36, v36, v37
	v_cvt_pk_bf16_f32 v37, v64, v65
	global_store_dwordx4 v[78:79], v[34:37], off offset:256
	s_nop 1
	v_mov_b32_e32 v34, v176
	s_waitcnt lgkmcnt(0)
; __device__ __forceinline__ unsigned pk2(float lo, float hi) { f32x2 v = {lo, hi}; bf16x2_t b = __builtin_convertvector(v, bf16x2_t); return __builtin_bit_cast(unsigned, b); }
;     __device__ __forceinline__ void operator()(f32x4 (&acc)[2][2][4][2], const Unit& u, int wr, int wc, int fr, int fq) const {
;     ...
; #pragma unroll
;             for (int ai = 0; ai < 2; ++ai)
; #pragma unroll
;                 for (int m = 0; m < 4; ++m) {
;                     const int rl = ai * HALF + wr * 64 + m * 16 + fr; const float r = S[rl];
;                     const f32x4 h0 = (acc[ai][bj][m][0] * r) * mp[0] + sh[0], h1 = (acc[ai][bj][m][1] * r) * mp[1] + sh[1];
;                     u32x4 w; w.x = pk2(h0[0], h0[1]); w.y = pk2(h0[2], h0[3]); w.z = pk2(h1[0], h1[1]); w.w = pk2(h1[2], h1[3]);
;                     *(u32x4*)(XN + (size_t)(u.pm * BM + rl) * DM + col) = w;
;                 }
	v_pk_mul_f32 v[64:65], v[94:95], v[34:35] op_sel_hi:[1,0]
	v_pk_mul_f32 v[36:37], v[96:97], v[34:35] op_sel_hi:[1,0]
	v_pk_mul_f32 v[70:71], v[132:133], v[34:35] op_sel_hi:[1,0]
	v_pk_mul_f32 v[34:35], v[130:131], v[34:35] op_sel_hi:[1,0]
	v_pk_fma_f32 v[36:37], v[48:49], v[36:37], v[32:33]
	v_pk_fma_f32 v[64:65], v[50:51], v[64:65], v[30:31]
	v_pk_fma_f32 v[70:71], v[52:53], v[70:71], v[28:29]
	v_pk_fma_f32 v[72:73], v[54:55], v[34:35], v[26:27]
	v_cvt_pk_bf16_f32 v34, v64, v65
	v_cvt_pk_bf16_f32 v35, v36, v37
	v_cvt_pk_bf16_f32 v36, v72, v73
	v_cvt_pk_bf16_f32 v37, v70, v71
	global_store_dwordx4 v[98:99], v[34:37], off offset:256
	s_nop 1
	v_mov_b32_e32 v34, v177
	s_waitcnt lgkmcnt(0)
	v_pk_mul_f32 v[64:65], v[90:91], v[34:35] op_sel_hi:[1,0]
	v_pk_mul_f32 v[36:37], v[92:93], v[34:35] op_sel_hi:[1,0]
	v_pk_mul_f32 v[70:71], v[136:137], v[34:35] op_sel_hi:[1,0]
	v_pk_mul_f32 v[34:35], v[134:135], v[34:35] op_sel_hi:[1,0]
	v_pk_fma_f32 v[36:37], v[48:49], v[36:37], v[32:33]
	v_pk_fma_f32 v[64:65], v[50:51], v[64:65], v[30:31]
	v_pk_fma_f32 v[70:71], v[52:53], v[70:71], v[28:29]
	v_pk_fma_f32 v[72:73], v[54:55], v[34:35], v[26:27]
	v_cvt_pk_bf16_f32 v34, v64, v65
	v_cvt_pk_bf16_f32 v35, v36, v37
	v_cvt_pk_bf16_f32 v36, v72, v73
	v_cvt_pk_bf16_f32 v37, v70, v71
	global_store_dwordx4 v[74:75], v[34:37], off offset:256
	s_nop 1
	v_mov_b32_e32 v34, v198
	s_waitcnt lgkmcnt(0)
	v_pk_mul_f32 v[64:65], v[82:83], v[34:35] op_sel_hi:[1,0]
	v_pk_mul_f32 v[36:37], v[84:85], v[34:35] op_sel_hi:[1,0]
	v_pk_mul_f32 v[24:25], v[24:25], v[34:35] op_sel_hi:[1,0]
	v_pk_mul_f32 v[22:23], v[22:23], v[34:35] op_sel_hi:[1,0]
	v_pk_fma_f32 v[36:37], v[48:49], v[36:37], v[32:33]
	v_pk_fma_f32 v[64:65], v[50:51], v[64:65], v[30:31]
	v_pk_fma_f32 v[34:35], v[52:53], v[24:25], v[28:29]
	v_pk_fma_f32 v[24:25], v[54:55], v[22:23], v[26:27]
	v_cvt_pk_bf16_f32 v22, v64, v65
	v_cvt_pk_bf16_f32 v23, v36, v37
	v_cvt_pk_bf16_f32 v24, v24, v25
	v_cvt_pk_bf16_f32 v25, v34, v35
	global_store_dwordx4 v[62:63], v[22:25], off offset:256
	s_nop 1
	v_mov_b32_e32 v22, v199
	s_waitcnt lgkmcnt(0)
	v_pk_mul_f32 v[34:35], v[66:67], v[22:23] op_sel_hi:[1,0]
	v_pk_mul_f32 v[24:25], v[68:69], v[22:23] op_sel_hi:[1,0]
	v_pk_mul_f32 v[16:17], v[16:17], v[22:23] op_sel_hi:[1,0]
	v_pk_mul_f32 v[14:15], v[14:15], v[22:23] op_sel_hi:[1,0]
	v_pk_fma_f32 v[24:25], v[48:49], v[24:25], v[32:33]
	v_pk_fma_f32 v[34:35], v[50:51], v[34:35], v[30:31]
	v_pk_fma_f32 v[22:23], v[52:53], v[16:17], v[28:29]
	v_pk_fma_f32 v[16:17], v[54:55], v[14:15], v[26:27]
	v_cvt_pk_bf16_f32 v14, v34, v35
	v_cvt_pk_bf16_f32 v15, v24, v25
	v_cvt_pk_bf16_f32 v16, v16, v17
	v_cvt_pk_bf16_f32 v17, v22, v23
	global_store_dwordx4 v[58:59], v[14:17], off offset:256
	s_nop 1
	v_mov_b32_e32 v14, v200
	s_waitcnt lgkmcnt(0)
	v_pk_mul_f32 v[22:23], v[42:43], v[14:15] op_sel_hi:[1,0]
	v_pk_mul_f32 v[16:17], v[44:45], v[14:15] op_sel_hi:[1,0]
	v_pk_mul_f32 v[10:11], v[10:11], v[14:15] op_sel_hi:[1,0]
	v_pk_mul_f32 v[8:9], v[8:9], v[14:15] op_sel_hi:[1,0]
	v_pk_fma_f32 v[16:17], v[48:49], v[16:17], v[32:33]
	v_pk_fma_f32 v[22:23], v[50:51], v[22:23], v[30:31]
	v_pk_fma_f32 v[14:15], v[52:53], v[10:11], v[28:29]
	v_pk_fma_f32 v[10:11], v[54:55], v[8:9], v[26:27]
	v_cvt_pk_bf16_f32 v8, v22, v23
	v_cvt_pk_bf16_f32 v9, v16, v17
	v_cvt_pk_bf16_f32 v10, v10, v11
	v_cvt_pk_bf16_f32 v11, v14, v15
	global_store_dwordx4 v[56:57], v[8:11], off offset:256
	s_nop 1
	v_mov_b32_e32 v8, v201
	s_waitcnt lgkmcnt(0)
	v_pk_mul_f32 v[14:15], v[38:39], v[8:9] op_sel_hi:[1,0]
	v_pk_mul_f32 v[10:11], v[40:41], v[8:9] op_sel_hi:[1,0]
	v_pk_mul_f32 v[6:7], v[6:7], v[8:9] op_sel_hi:[1,0]
	v_pk_mul_f32 v[4:5], v[4:5], v[8:9] op_sel_hi:[1,0]
	v_pk_fma_f32 v[10:11], v[48:49], v[10:11], v[32:33]
	v_pk_fma_f32 v[14:15], v[50:51], v[14:15], v[30:31]
	v_pk_fma_f32 v[8:9], v[52:53], v[6:7], v[28:29]
	v_pk_fma_f32 v[6:7], v[54:55], v[4:5], v[26:27]
	v_cvt_pk_bf16_f32 v4, v14, v15
	v_cvt_pk_bf16_f32 v5, v10, v11
	v_cvt_pk_bf16_f32 v6, v6, v7
	v_cvt_pk_bf16_f32 v7, v8, v9
	global_store_dwordx4 v[60:61], v[4:7], off offset:256
	s_nop 1
	v_mov_b32_e32 v4, v202
	s_waitcnt lgkmcnt(0)
	v_pk_mul_f32 v[8:9], v[18:19], v[4:5] op_sel_hi:[1,0]
	v_pk_mul_f32 v[6:7], v[20:21], v[4:5] op_sel_hi:[1,0]
	v_pk_mul_f32 v[2:3], v[2:3], v[4:5] op_sel_hi:[1,0]
	v_pk_mul_f32 v[0:1], v[0:1], v[4:5] op_sel_hi:[1,0]
	v_pk_fma_f32 v[6:7], v[48:49], v[6:7], v[32:33]
	v_pk_fma_f32 v[8:9], v[50:51], v[8:9], v[30:31]
	v_pk_fma_f32 v[4:5], v[52:53], v[2:3], v[28:29]
	v_pk_fma_f32 v[2:3], v[54:55], v[0:1], v[26:27]
	v_cvt_pk_bf16_f32 v0, v8, v9
	v_cvt_pk_bf16_f32 v1, v6, v7
	v_cvt_pk_bf16_f32 v2, v2, v3
	v_cvt_pk_bf16_f32 v3, v4, v5
	global_store_dwordx4 v[46:47], v[0:3], off offset:256
